# grid-barrier poll loops without back-off (s_sleep 0 instead of s_sleep 1)
# speedup vs baseline: 1.0031x; 1.0000x over previous
.LBB0_210:
	global_load_dword v15, v16, s[8:9] sc1
	s_waitcnt lgkmcnt(0)
	global_load_dword v0, v16, s[10:11] sc1
	global_load_dword v1, v16, s[12:13] sc1
	global_load_dword v2, v16, s[14:15] sc1
	global_load_dword v3, v16, s[20:21] sc1
	global_load_dword v4, v16, s[28:29] sc1
	global_load_dword v5, v16, s[36:37] sc1
	global_load_dword v6, v16, s[38:39] sc1
	global_load_dword v7, v16, s[40:41] sc1
	global_load_dword v8, v16, s[42:43] sc1
	global_load_dword v9, v16, s[44:45] sc1
	global_load_dword v10, v16, s[46:47] sc1
	global_load_dword v11, v16, s[48:49] sc1
	global_load_dword v12, v16, s[50:51] sc1
	global_load_dword v13, v16, s[52:53] sc1
	global_load_dword v14, v16, s[54:55] sc1
	s_mov_b64 s[56:57], -1
	s_mov_b64 s[58:59], -1
	s_waitcnt vmcnt(14)
	v_add_u32_e32 v17, v0, v15
	s_waitcnt vmcnt(13)
	v_add_u32_e32 v17, v17, v1
	s_waitcnt vmcnt(12)
	v_add_u32_e32 v17, v17, v2
	s_waitcnt vmcnt(11)
	v_add_u32_e32 v17, v17, v3
	s_waitcnt vmcnt(10)
	v_add_u32_e32 v17, v17, v4
	s_waitcnt vmcnt(9)
	v_add_u32_e32 v17, v17, v5
	s_waitcnt vmcnt(8)
	v_add_u32_e32 v17, v17, v6
	s_waitcnt vmcnt(7)
	v_add_u32_e32 v17, v17, v7
	s_waitcnt vmcnt(6)
	v_add_u32_e32 v17, v17, v8
	s_waitcnt vmcnt(5)
	v_add_u32_e32 v17, v17, v9
	s_waitcnt vmcnt(4)
	v_add_u32_e32 v17, v17, v10
	s_waitcnt vmcnt(3)
	v_add_u32_e32 v17, v17, v11
	s_waitcnt vmcnt(2)
	v_add_u32_e32 v17, v17, v12
	s_waitcnt vmcnt(1)
	v_add_u32_e32 v17, v17, v13
	s_waitcnt vmcnt(0)
	v_add_u32_e32 v17, v17, v14
	v_cmp_eq_u32_e32 vcc, s3, v17
	s_cbranch_vccnz .LBB0_209
	s_and_b32 s56, s62, 0xff
	s_cmp_eq_u32 s56, 0
	s_mov_b64 s[56:57], -1
	s_mov_b64 s[60:61], -1
	s_sleep 0
	s_cbranch_scc1 .LBB0_214
	s_and_b64 vcc, exec, s[60:61]
	s_cbranch_vccz .LBB0_209

.LBB0_228:
	s_and_b32 s38, s3, 0xff
	s_mov_b64 s[36:37], -1
	s_cmp_lg_u32 s38, 0
	s_mov_b64 s[40:41], -1
	s_sleep 0
	s_cbranch_scc0 .LBB0_231
	s_and_b64 vcc, exec, s[40:41]
	s_cbranch_vccz .LBB0_227

.LBB0_245:
	s_and_b32 s36, s3, 0xff
	s_cmp_lg_u32 s36, 0
	s_mov_b64 s[38:39], -1
	s_sleep 0
	s_cbranch_scc0 .LBB0_248
	s_mov_b64 s[40:41], -1
	s_and_b64 vcc, exec, s[38:39]
	s_cbranch_vccz .LBB0_244

.LBB0_355:
	global_load_dword v15, v16, s[10:11] sc1
	s_waitcnt lgkmcnt(0)
	global_load_dword v0, v16, s[20:21] sc1
	global_load_dword v1, v16, s[28:29] sc1
	global_load_dword v2, v16, s[36:37] sc1
	global_load_dword v3, v16, s[38:39] sc1
	global_load_dword v4, v16, s[40:41] sc1
	global_load_dword v5, v16, s[42:43] sc1
	global_load_dword v6, v16, s[44:45] sc1
	global_load_dword v7, v16, s[46:47] sc1
	global_load_dword v8, v16, s[48:49] sc1
	global_load_dword v9, v16, s[50:51] sc1
	global_load_dword v10, v16, s[52:53] sc1
	global_load_dword v11, v16, s[54:55] sc1
	global_load_dword v12, v16, s[56:57] sc1
	global_load_dword v13, v16, s[58:59] sc1
	global_load_dword v14, v16, s[60:61] sc1
	s_mov_b64 s[62:63], -1
	s_mov_b64 s[64:65], -1
	s_waitcnt vmcnt(14)
	v_add_u32_e32 v17, v0, v15
	s_waitcnt vmcnt(13)
	v_add_u32_e32 v17, v17, v1
	s_waitcnt vmcnt(12)
	v_add_u32_e32 v17, v17, v2
	s_waitcnt vmcnt(11)
	v_add_u32_e32 v17, v17, v3
	s_waitcnt vmcnt(10)
	v_add_u32_e32 v17, v17, v4
	s_waitcnt vmcnt(9)
	v_add_u32_e32 v17, v17, v5
	s_waitcnt vmcnt(8)
	v_add_u32_e32 v17, v17, v6
	s_waitcnt vmcnt(7)
	v_add_u32_e32 v17, v17, v7
	s_waitcnt vmcnt(6)
	v_add_u32_e32 v17, v17, v8
	s_waitcnt vmcnt(5)
	v_add_u32_e32 v17, v17, v9
	s_waitcnt vmcnt(4)
	v_add_u32_e32 v17, v17, v10
	s_waitcnt vmcnt(3)
	v_add_u32_e32 v17, v17, v11
	s_waitcnt vmcnt(2)
	v_add_u32_e32 v17, v17, v12
	s_waitcnt vmcnt(1)
	v_add_u32_e32 v17, v17, v13
	s_waitcnt vmcnt(0)
	v_add_u32_e32 v17, v17, v14
	v_cmp_eq_u32_e32 vcc, s3, v17
	s_cbranch_vccnz .LBB0_354
	s_and_b32 s62, s68, 0xff
	s_cmp_eq_u32 s62, 0
	s_mov_b64 s[62:63], -1
	s_mov_b64 s[66:67], -1
	s_sleep 0
	s_cbranch_scc1 .LBB0_359
	s_and_b64 vcc, exec, s[66:67]
	s_cbranch_vccz .LBB0_354

.LBB0_373:
	s_and_b32 s44, s3, 0xff
	s_mov_b64 s[42:43], -1
	s_cmp_lg_u32 s44, 0
	s_mov_b64 s[46:47], -1
	s_sleep 0
	s_cbranch_scc0 .LBB0_376
	s_and_b64 vcc, exec, s[46:47]
	s_cbranch_vccz .LBB0_372

.LBB0_390:
	s_and_b32 s42, s3, 0xff
	s_cmp_lg_u32 s42, 0
	s_mov_b64 s[44:45], -1
	s_sleep 0
	s_cbranch_scc0 .LBB0_393
	s_mov_b64 s[46:47], -1
	s_and_b64 vcc, exec, s[44:45]
	s_cbranch_vccz .LBB0_389

.LBB0_486:
	global_load_dword v15, v16, s[8:9] sc1
	s_waitcnt lgkmcnt(0)
	global_load_dword v0, v16, s[10:11] sc1
	global_load_dword v1, v16, s[20:21] sc1
	global_load_dword v2, v16, s[28:29] sc1
	global_load_dword v3, v16, s[36:37] sc1
	global_load_dword v4, v16, s[38:39] sc1
	global_load_dword v5, v16, s[40:41] sc1
	global_load_dword v6, v16, s[42:43] sc1
	global_load_dword v7, v16, s[44:45] sc1
	global_load_dword v8, v16, s[46:47] sc1
	global_load_dword v9, v16, s[48:49] sc1
	global_load_dword v10, v16, s[50:51] sc1
	global_load_dword v11, v16, s[52:53] sc1
	global_load_dword v12, v16, s[54:55] sc1
	global_load_dword v13, v16, s[56:57] sc1
	global_load_dword v14, v16, s[58:59] sc1
	s_mov_b64 s[60:61], -1
	s_mov_b64 s[62:63], -1
	s_waitcnt vmcnt(14)
	v_add_u32_e32 v17, v0, v15
	s_waitcnt vmcnt(13)
	v_add_u32_e32 v17, v17, v1
	s_waitcnt vmcnt(12)
	v_add_u32_e32 v17, v17, v2
	s_waitcnt vmcnt(11)
	v_add_u32_e32 v17, v17, v3
	s_waitcnt vmcnt(10)
	v_add_u32_e32 v17, v17, v4
	s_waitcnt vmcnt(9)
	v_add_u32_e32 v17, v17, v5
	s_waitcnt vmcnt(8)
	v_add_u32_e32 v17, v17, v6
	s_waitcnt vmcnt(7)
	v_add_u32_e32 v17, v17, v7
	s_waitcnt vmcnt(6)
	v_add_u32_e32 v17, v17, v8
	s_waitcnt vmcnt(5)
	v_add_u32_e32 v17, v17, v9
	s_waitcnt vmcnt(4)
	v_add_u32_e32 v17, v17, v10
	s_waitcnt vmcnt(3)
	v_add_u32_e32 v17, v17, v11
	s_waitcnt vmcnt(2)
	v_add_u32_e32 v17, v17, v12
	s_waitcnt vmcnt(1)
	v_add_u32_e32 v17, v17, v13
	s_waitcnt vmcnt(0)
	v_add_u32_e32 v17, v17, v14
	v_cmp_eq_u32_e32 vcc, s3, v17
	s_cbranch_vccnz .LBB0_485
	s_and_b32 s60, s66, 0xff
	s_cmp_eq_u32 s60, 0
	s_mov_b64 s[60:61], -1
	s_mov_b64 s[64:65], -1
	s_sleep 0
	s_cbranch_scc1 .LBB0_490
	s_and_b64 vcc, exec, s[64:65]
	s_cbranch_vccz .LBB0_485

.LBB0_504:
	s_and_b32 s42, s3, 0xff
	s_mov_b64 s[40:41], -1
	s_cmp_lg_u32 s42, 0
	s_mov_b64 s[44:45], -1
	s_sleep 0
	s_cbranch_scc0 .LBB0_507
	s_and_b64 vcc, exec, s[44:45]
	s_cbranch_vccz .LBB0_503

.LBB0_521:
	s_and_b32 s40, s3, 0xff
	s_cmp_lg_u32 s40, 0
	s_mov_b64 s[42:43], -1
	s_sleep 0
	s_cbranch_scc0 .LBB0_524
	s_mov_b64 s[44:45], -1
	s_and_b64 vcc, exec, s[42:43]
	s_cbranch_vccz .LBB0_520

.LBB0_751:
	global_load_dword v15, v16, s[6:7] sc1
	s_waitcnt lgkmcnt(0)
	global_load_dword v0, v16, s[8:9] sc1
	global_load_dword v1, v16, s[10:11] sc1
	global_load_dword v2, v16, s[20:21] sc1
	global_load_dword v3, v16, s[28:29] sc1
	global_load_dword v4, v16, s[36:37] sc1
	global_load_dword v5, v16, s[38:39] sc1
	global_load_dword v6, v16, s[40:41] sc1
	global_load_dword v7, v16, s[42:43] sc1
	global_load_dword v8, v16, s[44:45] sc1
	global_load_dword v9, v16, s[46:47] sc1
	global_load_dword v10, v16, s[48:49] sc1
	global_load_dword v11, v16, s[50:51] sc1
	global_load_dword v12, v16, s[52:53] sc1
	global_load_dword v13, v16, s[54:55] sc1
	global_load_dword v14, v16, s[56:57] sc1
	s_mov_b64 s[58:59], -1
	s_mov_b64 s[60:61], -1
	s_waitcnt vmcnt(14)
	v_add_u32_e32 v17, v0, v15
	s_waitcnt vmcnt(13)
	v_add_u32_e32 v17, v17, v1
	s_waitcnt vmcnt(12)
	v_add_u32_e32 v17, v17, v2
	s_waitcnt vmcnt(11)
	v_add_u32_e32 v17, v17, v3
	s_waitcnt vmcnt(10)
	v_add_u32_e32 v17, v17, v4
	s_waitcnt vmcnt(9)
	v_add_u32_e32 v17, v17, v5
	s_waitcnt vmcnt(8)
	v_add_u32_e32 v17, v17, v6
	s_waitcnt vmcnt(7)
	v_add_u32_e32 v17, v17, v7
	s_waitcnt vmcnt(6)
	v_add_u32_e32 v17, v17, v8
	s_waitcnt vmcnt(5)
	v_add_u32_e32 v17, v17, v9
	s_waitcnt vmcnt(4)
	v_add_u32_e32 v17, v17, v10
	s_waitcnt vmcnt(3)
	v_add_u32_e32 v17, v17, v11
	s_waitcnt vmcnt(2)
	v_add_u32_e32 v17, v17, v12
	s_waitcnt vmcnt(1)
	v_add_u32_e32 v17, v17, v13
	s_waitcnt vmcnt(0)
	v_add_u32_e32 v17, v17, v14
	v_cmp_eq_u32_e32 vcc, s3, v17
	s_cbranch_vccnz .LBB0_750
	s_and_b32 s58, s64, 0xff
	s_cmp_eq_u32 s58, 0
	s_mov_b64 s[58:59], -1
	s_mov_b64 s[62:63], -1
	s_sleep 0
	s_cbranch_scc1 .LBB0_755
	s_and_b64 vcc, exec, s[62:63]
	s_cbranch_vccz .LBB0_750

.LBB0_769:
	s_and_b32 s40, s3, 0xff
	s_mov_b64 s[38:39], -1
	s_cmp_lg_u32 s40, 0
	s_mov_b64 s[42:43], -1
	s_sleep 0
	s_cbranch_scc0 .LBB0_772
	s_and_b64 vcc, exec, s[42:43]
	s_cbranch_vccz .LBB0_768

.LBB0_786:
	s_and_b32 s38, s3, 0xff
	s_cmp_lg_u32 s38, 0
	s_mov_b64 s[40:41], -1
	s_sleep 0
	s_cbranch_scc0 .LBB0_789
	s_mov_b64 s[42:43], -1
	s_and_b64 vcc, exec, s[40:41]
	s_cbranch_vccz .LBB0_785

.LBB0_1047:
	global_load_dword v15, v16, s[8:9] sc1
	s_waitcnt lgkmcnt(0)
	global_load_dword v0, v16, s[10:11] sc1
	global_load_dword v1, v16, s[16:17] sc1
	global_load_dword v2, v16, s[18:19] sc1
	global_load_dword v3, v16, s[20:21] sc1
	global_load_dword v4, v16, s[28:29] sc1
	global_load_dword v5, v16, s[36:37] sc1
	global_load_dword v6, v16, s[38:39] sc1
	global_load_dword v7, v16, s[40:41] sc1
	global_load_dword v8, v16, s[42:43] sc1
	global_load_dword v9, v16, s[44:45] sc1
	global_load_dword v10, v16, s[46:47] sc1
	global_load_dword v11, v16, s[48:49] sc1
	global_load_dword v12, v16, s[50:51] sc1
	global_load_dword v13, v16, s[52:53] sc1
	global_load_dword v14, v16, s[54:55] sc1
	s_mov_b64 s[56:57], -1
	s_mov_b64 s[58:59], -1
	s_waitcnt vmcnt(14)
	v_add_u32_e32 v17, v0, v15
	s_waitcnt vmcnt(13)
	v_add_u32_e32 v17, v17, v1
	s_waitcnt vmcnt(12)
	v_add_u32_e32 v17, v17, v2
	s_waitcnt vmcnt(11)
	v_add_u32_e32 v17, v17, v3
	s_waitcnt vmcnt(10)
	v_add_u32_e32 v17, v17, v4
	s_waitcnt vmcnt(9)
	v_add_u32_e32 v17, v17, v5
	s_waitcnt vmcnt(8)
	v_add_u32_e32 v17, v17, v6
	s_waitcnt vmcnt(7)
	v_add_u32_e32 v17, v17, v7
	s_waitcnt vmcnt(6)
	v_add_u32_e32 v17, v17, v8
	s_waitcnt vmcnt(5)
	v_add_u32_e32 v17, v17, v9
	s_waitcnt vmcnt(4)
	v_add_u32_e32 v17, v17, v10
	s_waitcnt vmcnt(3)
	v_add_u32_e32 v17, v17, v11
	s_waitcnt vmcnt(2)
	v_add_u32_e32 v17, v17, v12
	s_waitcnt vmcnt(1)
	v_add_u32_e32 v17, v17, v13
	s_waitcnt vmcnt(0)
	v_add_u32_e32 v17, v17, v14
	v_cmp_eq_u32_e32 vcc, s3, v17
	s_cbranch_vccnz .LBB0_1046
	s_and_b32 s56, s62, 0xff
	s_cmp_eq_u32 s56, 0
	s_mov_b64 s[56:57], -1
	s_mov_b64 s[60:61], -1
	s_sleep 0
	s_cbranch_scc1 .LBB0_1051
	s_and_b64 vcc, exec, s[60:61]
	s_cbranch_vccz .LBB0_1046

.LBB0_1132:
	global_load_dword v15, v16, s[8:9] sc1
	s_waitcnt lgkmcnt(0)
	global_load_dword v0, v16, s[10:11] sc1
	global_load_dword v1, v16, s[16:17] sc1
	global_load_dword v2, v16, s[18:19] sc1
	global_load_dword v3, v16, s[20:21] sc1
	global_load_dword v4, v16, s[28:29] sc1
	global_load_dword v5, v16, s[36:37] sc1
	global_load_dword v6, v16, s[38:39] sc1
	global_load_dword v7, v16, s[40:41] sc1
	global_load_dword v8, v16, s[42:43] sc1
	global_load_dword v9, v16, s[44:45] sc1
	global_load_dword v10, v16, s[46:47] sc1
	global_load_dword v11, v16, s[48:49] sc1
	global_load_dword v12, v16, s[50:51] sc1
	global_load_dword v13, v16, s[52:53] sc1
	global_load_dword v14, v16, s[54:55] sc1
	s_mov_b64 s[56:57], -1
	s_mov_b64 s[58:59], -1
	s_waitcnt vmcnt(14)
	v_add_u32_e32 v17, v0, v15
	s_waitcnt vmcnt(13)
	v_add_u32_e32 v17, v17, v1
	s_waitcnt vmcnt(12)
	v_add_u32_e32 v17, v17, v2
	s_waitcnt vmcnt(11)
	v_add_u32_e32 v17, v17, v3
	s_waitcnt vmcnt(10)
	v_add_u32_e32 v17, v17, v4
	s_waitcnt vmcnt(9)
	v_add_u32_e32 v17, v17, v5
	s_waitcnt vmcnt(8)
	v_add_u32_e32 v17, v17, v6
	s_waitcnt vmcnt(7)
	v_add_u32_e32 v17, v17, v7
	s_waitcnt vmcnt(6)
	v_add_u32_e32 v17, v17, v8
	s_waitcnt vmcnt(5)
	v_add_u32_e32 v17, v17, v9
	s_waitcnt vmcnt(4)
	v_add_u32_e32 v17, v17, v10
	s_waitcnt vmcnt(3)
	v_add_u32_e32 v17, v17, v11
	s_waitcnt vmcnt(2)
	v_add_u32_e32 v17, v17, v12
	s_waitcnt vmcnt(1)
	v_add_u32_e32 v17, v17, v13
	s_waitcnt vmcnt(0)
	v_add_u32_e32 v17, v17, v14
	v_cmp_eq_u32_e32 vcc, s3, v17
	s_cbranch_vccnz .LBB0_1131
	s_and_b32 s35, s31, 0xff
	s_cmp_eq_u32 s35, 0
	s_mov_b64 s[60:61], -1
	s_sleep 0
	s_cbranch_scc1 .LBB0_1136
	s_and_b64 vcc, exec, s[60:61]
	s_cbranch_vccz .LBB0_1131

.LBB0_1150:
	s_and_b32 s31, s3, 0xff
	s_mov_b64 s[36:37], -1
	s_cmp_lg_u32 s31, 0
	s_mov_b64 s[40:41], -1
	s_sleep 0
	s_cbranch_scc0 .LBB0_1153
	s_and_b64 vcc, exec, s[40:41]
	s_cbranch_vccz .LBB0_1149

.LBB0_1167:
	s_and_b32 s31, s3, 0xff
	s_cmp_lg_u32 s31, 0
	s_mov_b64 s[38:39], -1
	s_sleep 0
	s_cbranch_scc0 .LBB0_1170
	s_mov_b64 s[40:41], -1
	s_and_b64 vcc, exec, s[38:39]
	s_cbranch_vccz .LBB0_1166
